# ATTN ping-pong + section 7.11 back-edge rotation: head barrier right after COMPUTE, ring advance / exit test / tile set-up / mask conversion moved behind it into the LOAD side
# baseline (speedup 1.0000x reference)
.LBB0_954:
	s_waitcnt vmcnt(0)
	s_waitcnt lgkmcnt(0)
	s_barrier
	s_add_i32 s5, s34, 1
	s_cmp_lg_u32 s34, 2
	s_cselect_b32 s34, s5, 0
	s_addk_i32 s31, 0xff00
	s_add_i32 s15, s15, 1
	s_add_i32 s5, s30, s31
	s_add_i32 s33, s33, 64
	s_cmp_eq_u32 s5, 0
	s_cbranch_scc1 .LBB0_946
	s_branch .Lpp_hd
.LBB0_955:
	s_waitcnt vmcnt(0)
	s_waitcnt lgkmcnt(0)
	s_barrier
.Lpp_hd:
	s_add_i32 s35, s15, -2
	s_lshl_b32 s5, s34, 13
	s_cmp_lt_u32 s15, s27
	s_cselect_b32 s10, s15, s29
	s_lshl_b64 s[6:7], s[10:11], 16
	v_lshrrev_b32_e32 v3, v1, v138
	v_lshl_add_u64 v[6:7], v[116:117], 0, s[6:7]
	v_lshl_add_u64 v[8:9], v[118:119], 0, s[6:7]
	s_add_i32 s6, s5, 0xffffe000
	v_lshlrev_b32_e32 v3, 4, v3
	s_cmp_lg_u32 s34, 0
	v_and_b32_e32 v4, 0xf0f0f0f0, v3
	v_lshrrev_b32_e32 v3, v1, v139
	s_cselect_b32 s6, s6, 0x4000
	v_lshlrev_b32_e32 v3, 4, v3
	s_add_i32 s6, s6, 0
	v_and_b32_e32 v3, 0xf0f0f0f0, v3
	s_add_i32 s6, s20, s6
	s_add_i32 s7, s6, 0x6000
	s_mov_b32 m0, s6
	global_load_lds_dwordx4 v[6:7], off
	s_mov_b32 m0, s7
	global_load_lds_dwordx4 v[8:9], off
	s_add_i32 s6, s15, -1
	s_cmp_lt_u32 s35, 63
	s_cselect_b32 s10, s6, 63
	s_lshl_b64 s[6:7], s[10:11], 15
	v_lshl_add_u64 v[6:7], v[136:137], 0, s[6:7]
	global_load_dwordx2 v[138:139], v[6:7], off
	s_cmp_gt_u32 s35, s28
	s_cbranch_scc1 .Lpp_skip
	v_add_u32_e32 v149, s5, v140
	v_add_u32_e32 v150, s5, v141
	v_add_u32_sdwa v230, v4, s25 dst_sel:DWORD dst_unused:UNUSED_PAD src0_sel:BYTE_0 src1_sel:DWORD
	v_add_u32_sdwa v231, v4, s25 dst_sel:DWORD dst_unused:UNUSED_PAD src0_sel:BYTE_1 src1_sel:DWORD
	v_add_u32_sdwa v232, v4, s25 dst_sel:DWORD dst_unused:UNUSED_PAD src0_sel:BYTE_2 src1_sel:DWORD
	v_add_u32_sdwa v233, v4, s25 dst_sel:DWORD dst_unused:UNUSED_PAD src0_sel:BYTE_3 src1_sel:DWORD
	v_add_u32_sdwa v234, v3, s25 dst_sel:DWORD dst_unused:UNUSED_PAD src0_sel:BYTE_0 src1_sel:DWORD
	v_add_u32_sdwa v235, v3, s25 dst_sel:DWORD dst_unused:UNUSED_PAD src0_sel:BYTE_1 src1_sel:DWORD
	v_add_u32_sdwa v236, v3, s25 dst_sel:DWORD dst_unused:UNUSED_PAD src0_sel:BYTE_2 src1_sel:DWORD
	v_add_u32_sdwa v237, v3, s25 dst_sel:DWORD dst_unused:UNUSED_PAD src0_sel:BYTE_3 src1_sel:DWORD
	ds_read_b128 v[66:69], v230
	ds_read_b128 v[70:73], v231
	ds_read_b128 v[74:77], v232
	ds_read_b128 v[78:81], v233
	ds_read_b128 v[182:185], v149
	ds_read_b128 v[186:189], v149 offset:2048
	ds_read_b128 v[190:193], v149 offset:4096
	ds_read_b128 v[194:197], v149 offset:6144
	ds_read_b128 v[82:85], v234
	ds_read_b128 v[86:89], v235
	ds_read_b128 v[90:93], v236
	ds_read_b128 v[94:97], v237
	s_waitcnt lgkmcnt(8)
	ds_read_b128 v[198:201], v149 offset:512
	ds_read_b128 v[202:205], v149 offset:2560
	ds_read_b128 v[206:209], v149 offset:4608
	ds_read_b128 v[210:213], v149 offset:6656
	s_waitcnt lgkmcnt(8)
	ds_read_b64_tr_b16 v[152:153], v150
	ds_read_b64_tr_b16 v[154:155], v150 offset:512
	ds_read_b64_tr_b16 v[156:157], v150 offset:1024
	ds_read_b64_tr_b16 v[158:159], v150 offset:1536
	s_waitcnt lgkmcnt(8)
	ds_read_b64_tr_b16 v[160:161], v150 offset:2048
	ds_read_b64_tr_b16 v[162:163], v150 offset:2560
	ds_read_b64_tr_b16 v[164:165], v150 offset:3072
	ds_read_b64_tr_b16 v[166:167], v150 offset:3584
	s_waitcnt lgkmcnt(8)
	ds_read_b64_tr_b16 v[168:169], v150 offset:4096
	ds_read_b64_tr_b16 v[170:171], v150 offset:4608
	ds_read_b64_tr_b16 v[172:173], v150 offset:5120
	ds_read_b64_tr_b16 v[174:175], v150 offset:5632
	s_waitcnt lgkmcnt(8)
	ds_read_b64_tr_b16 v[214:215], v150 offset:6144
	ds_read_b64_tr_b16 v[216:217], v150 offset:6656
	ds_read_b64_tr_b16 v[218:219], v150 offset:7168
	ds_read_b64_tr_b16 v[220:221], v150 offset:7680
	s_waitcnt lgkmcnt(0)
	s_barrier
	v_mfma_f32_32x32x16_bf16 v[66:81], v[182:185], v[110:113], v[66:81]
	v_mfma_f32_32x32x16_bf16 v[66:81], v[186:189], v[98:101], v[66:81]
	v_mfma_f32_32x32x16_bf16 v[66:81], v[190:193], v[102:105], v[66:81]
	v_mfma_f32_32x32x16_bf16 v[66:81], v[194:197], v[106:109], v[66:81]
	s_cmp_lt_u32 s33, s14
	s_cbranch_scc0 .Lpp_bias
	v_mfma_f32_32x32x16_bf16 v[82:97], v[198:201], v[110:113], v[82:97]
	s_nop 5
	v_mfma_f32_32x32x16_bf16 v[82:97], v[202:205], v[98:101], v[82:97]
	s_nop 3
	v_exp_f32_e32 v66, v66
	v_mfma_f32_32x32x16_bf16 v[82:97], v[206:209], v[102:105], v[82:97]
	v_exp_f32_e32 v67, v67
	v_exp_f32_e32 v68, v68
	v_exp_f32_e32 v69, v69
	v_mfma_f32_32x32x16_bf16 v[82:97], v[210:213], v[106:109], v[82:97]
	v_exp_f32_e32 v70, v70
	v_exp_f32_e32 v71, v71
	v_exp_f32_e32 v72, v72
	v_exp_f32_e32 v73, v73
	v_cvt_pk_bf16_f32 v4, v66, v67
	v_cvt_pk_bf16_f32 v5, v68, v69
	v_cvt_pk_bf16_f32 v6, v70, v71
	v_cvt_pk_bf16_f32 v7, v72, v73
	s_nop 1
	v_mfma_f32_32x32x16_bf16 v[34:49], v[4:7], v[152:155], v[34:49]
	v_exp_f32_e32 v74, v74
	v_exp_f32_e32 v75, v75
	v_exp_f32_e32 v76, v76
	v_mfma_f32_32x32x16_bf16 v[18:33], v[4:7], v[168:171], v[18:33]
	v_exp_f32_e32 v77, v77
	v_exp_f32_e32 v78, v78
	v_exp_f32_e32 v79, v79
	v_mfma_f32_32x32x16_bf16 v[50:65], v[4:7], v[226:229], v[50:65]
	v_exp_f32_e32 v80, v80
	v_exp_f32_e32 v81, v81
	v_cvt_pk_bf16_f32 v8, v74, v75
	v_cvt_pk_bf16_f32 v9, v76, v77
	v_cvt_pk_bf16_f32 v10, v78, v79
	v_cvt_pk_bf16_f32 v11, v80, v81
	s_nop 1
	v_mfma_f32_32x32x16_bf16 v[34:49], v[8:11], v[156:159], v[34:49]
	v_exp_f32_e32 v82, v82
	v_exp_f32_e32 v83, v83
	v_exp_f32_e32 v84, v84
	v_mfma_f32_32x32x16_bf16 v[18:33], v[8:11], v[172:175], v[18:33]
	v_exp_f32_e32 v85, v85
	v_exp_f32_e32 v86, v86
	v_exp_f32_e32 v87, v87
	v_mfma_f32_32x32x16_bf16 v[50:65], v[8:11], v[226:229], v[50:65]
	v_exp_f32_e32 v88, v88
	v_exp_f32_e32 v89, v89
	v_cvt_pk_bf16_f32 v12, v82, v83
	v_cvt_pk_bf16_f32 v13, v84, v85
	v_cvt_pk_bf16_f32 v14, v86, v87
	v_cvt_pk_bf16_f32 v15, v88, v89
	s_nop 1
	v_mfma_f32_32x32x16_bf16 v[34:49], v[12:15], v[160:163], v[34:49]
	v_exp_f32_e32 v90, v90
	v_exp_f32_e32 v91, v91
	v_exp_f32_e32 v92, v92
	v_mfma_f32_32x32x16_bf16 v[18:33], v[12:15], v[214:217], v[18:33]
	v_exp_f32_e32 v93, v93
	v_exp_f32_e32 v94, v94
	v_exp_f32_e32 v95, v95
	v_mfma_f32_32x32x16_bf16 v[50:65], v[12:15], v[226:229], v[50:65]
	v_exp_f32_e32 v96, v96
	v_exp_f32_e32 v97, v97
	v_cvt_pk_bf16_f32 v222, v90, v91
	v_cvt_pk_bf16_f32 v223, v92, v93
	v_cvt_pk_bf16_f32 v224, v94, v95
	v_cvt_pk_bf16_f32 v225, v96, v97
	s_nop 1
	v_mfma_f32_32x32x16_bf16 v[34:49], v[222:225], v[164:167], v[34:49]
	v_mfma_f32_32x32x16_bf16 v[18:33], v[222:225], v[218:221], v[18:33]
	v_mfma_f32_32x32x16_bf16 v[50:65], v[222:225], v[226:229], v[50:65]
	s_branch .LBB0_954
